# grid barrier: XCD leaders poll the monotonic TOP arrival counter directly instead of waiting for the TOPGEN flag set by the last leader (one memory hop less)
# speedup vs baseline: 1.0209x; 1.0026x over previous
.LBB0_956:
	s_or_b64 exec, exec, s[16:17]
	s_waitcnt vmcnt(0)
	v_readfirstlane_b32 s2, v2
	v_cvt_f32_u32_e32 v2, v0
	v_sub_u32_e32 v3, 0, v0
	v_add_u32_e32 v1, s2, v1
	v_readlane_b32 s8, v252, 9
	v_rcp_iflag_f32_e32 v2, v2
	v_readlane_b32 s9, v252, 10
	s_mov_b64 s[16:17], -1
	v_mul_f32_e32 v2, 0x4f7ffffe, v2
	v_cvt_u32_f32_e32 v2, v2
	v_mul_lo_u32 v3, v3, v2
	v_mul_hi_u32 v3, v2, v3
	v_add_u32_e32 v2, v2, v3
	v_mul_hi_u32 v2, v1, v2
	v_mul_lo_u32 v3, v2, v0
	v_sub_u32_e32 v3, v1, v3
	v_cmp_ge_u32_e32 vcc, v3, v0
	v_add_u32_e32 v4, 1, v2
	v_add_u32_e32 v1, 1, v1
	v_cndmask_b32_e32 v2, v2, v4, vcc
	v_sub_u32_e32 v4, v3, v0
	v_cndmask_b32_e32 v3, v3, v4, vcc
	v_cmp_ge_u32_e32 vcc, v3, v0
	v_add_u32_e32 v3, 1, v2
	s_nop 0
	v_cndmask_b32_e32 v2, v2, v3, vcc
	v_mul_lo_u32 v3, v0, v2
	v_add_u32_e32 v0, v3, v0
	v_mov_b32_e32 v5, v0
	v_cmp_ne_u32_e32 vcc, v1, v0
	v_mov_b64_e32 v[0:1], s[8:9]
	s_and_saveexec_b64 s[14:15], vcc
	s_cbranch_execz .LBB0_968
	v_readlane_b32 s8, v252, 7
	v_readlane_b32 s9, v252, 8
	s_mov_b64 s[18:19], 0
	s_nop 3
	global_load_dword v0, v33, s[8:9] sc1
	s_waitcnt vmcnt(0)
	v_cmp_lt_u32_e32 vcc, v0, v5
	s_and_saveexec_b64 s[16:17], vcc
	s_cbranch_execz .LBB0_967
	s_mov_b32 s2, 1
	s_branch .LBB0_960

.LBB0_964:
	v_readlane_b32 s8, v252, 7
	v_readlane_b32 s9, v252, 8
	s_add_i32 s2, s2, 1
	s_mov_b64 s[34:35], -1
	s_nop 2
	global_load_dword v0, v33, s[8:9] sc1
	s_waitcnt vmcnt(0)
	v_cmp_ge_u32_e32 vcc, v0, v5
	s_orn2_b64 s[30:31], vcc, exec
	s_branch .LBB0_959

.LBB0_1610:
	s_or_b64 exec, exec, s[18:19]
	s_waitcnt vmcnt(0)
	v_readfirstlane_b32 s2, v2
	v_cvt_f32_u32_e32 v2, v0
	v_sub_u32_e32 v3, 0, v0
	v_add_u32_e32 v1, s2, v1
	v_readlane_b32 s8, v252, 9
	v_rcp_iflag_f32_e32 v2, v2
	v_readlane_b32 s9, v252, 10
	s_mov_b64 s[18:19], -1
	v_mul_f32_e32 v2, 0x4f7ffffe, v2
	v_cvt_u32_f32_e32 v2, v2
	v_mul_lo_u32 v3, v3, v2
	v_mul_hi_u32 v3, v2, v3
	v_add_u32_e32 v2, v2, v3
	v_mul_hi_u32 v2, v1, v2
	v_mul_lo_u32 v3, v2, v0
	v_sub_u32_e32 v3, v1, v3
	v_cmp_ge_u32_e32 vcc, v3, v0
	v_add_u32_e32 v4, 1, v2
	v_add_u32_e32 v1, 1, v1
	v_cndmask_b32_e32 v2, v2, v4, vcc
	v_sub_u32_e32 v4, v3, v0
	v_cndmask_b32_e32 v3, v3, v4, vcc
	v_cmp_ge_u32_e32 vcc, v3, v0
	v_add_u32_e32 v3, 1, v2
	s_nop 0
	v_cndmask_b32_e32 v2, v2, v3, vcc
	v_mul_lo_u32 v3, v0, v2
	v_add_u32_e32 v0, v3, v0
	v_mov_b32_e32 v5, v0
	v_cmp_ne_u32_e32 vcc, v1, v0
	v_mov_b64_e32 v[0:1], s[8:9]
	s_and_saveexec_b64 s[16:17], vcc
	s_cbranch_execz .LBB0_1622
	v_readlane_b32 s8, v252, 7
	v_readlane_b32 s9, v252, 8
	s_mov_b64 s[20:21], 0
	s_nop 3
	global_load_dword v0, v33, s[8:9] sc1
	s_waitcnt vmcnt(0)
	v_cmp_lt_u32_e32 vcc, v0, v5
	s_and_saveexec_b64 s[18:19], vcc
	s_cbranch_execz .LBB0_1621
	s_mov_b32 s2, 1
	s_branch .LBB0_1614

.LBB0_1618:
	v_readlane_b32 s8, v252, 7
	v_readlane_b32 s9, v252, 8
	s_add_i32 s2, s2, 1
	s_mov_b64 s[44:45], -1
	s_nop 2
	global_load_dword v0, v33, s[8:9] sc1
	s_waitcnt vmcnt(0)
	v_cmp_ge_u32_e32 vcc, v0, v5
	s_orn2_b64 s[34:35], vcc, exec
	s_branch .LBB0_1613

.LBB0_1730:
	s_or_b64 exec, exec, s[16:17]
	s_waitcnt vmcnt(0)
	v_readfirstlane_b32 s8, v2
	v_cvt_f32_u32_e32 v2, v0
	v_sub_u32_e32 v3, 0, v0
	v_add_u32_e32 v1, s8, v1
	v_readlane_b32 s8, v252, 9
	v_rcp_iflag_f32_e32 v2, v2
	v_readlane_b32 s9, v252, 10
	s_mov_b64 s[16:17], -1
	v_mul_f32_e32 v2, 0x4f7ffffe, v2
	v_cvt_u32_f32_e32 v2, v2
	v_mul_lo_u32 v3, v3, v2
	v_mul_hi_u32 v3, v2, v3
	v_add_u32_e32 v2, v2, v3
	v_mul_hi_u32 v2, v1, v2
	v_mul_lo_u32 v3, v2, v0
	v_sub_u32_e32 v3, v1, v3
	v_cmp_ge_u32_e32 vcc, v3, v0
	v_add_u32_e32 v4, 1, v2
	v_add_u32_e32 v1, 1, v1
	v_cndmask_b32_e32 v2, v2, v4, vcc
	v_sub_u32_e32 v4, v3, v0
	v_cndmask_b32_e32 v3, v3, v4, vcc
	v_cmp_ge_u32_e32 vcc, v3, v0
	v_add_u32_e32 v3, 1, v2
	s_nop 0
	v_cndmask_b32_e32 v2, v2, v3, vcc
	v_mul_lo_u32 v3, v0, v2
	v_add_u32_e32 v0, v3, v0
	v_mov_b32_e32 v5, v0
	v_cmp_ne_u32_e32 vcc, v1, v0
	v_mov_b64_e32 v[0:1], s[8:9]
	s_and_saveexec_b64 s[14:15], vcc
	s_cbranch_execz .LBB0_1742
	v_readlane_b32 s8, v252, 7
	v_readlane_b32 s9, v252, 8
	s_mov_b64 s[18:19], 0
	s_nop 3
	global_load_dword v0, v33, s[8:9] sc1
	s_waitcnt vmcnt(0)
	v_cmp_lt_u32_e32 vcc, v0, v5
	s_and_saveexec_b64 s[16:17], vcc
	s_cbranch_execz .LBB0_1741
	s_mov_b32 s8, 1
	s_branch .LBB0_1734

.LBB0_1738:
	v_readlane_b32 s30, v252, 7
	v_readlane_b32 s31, v252, 8
	s_add_i32 s8, s8, 1
	s_mov_b64 s[34:35], -1
	s_nop 2
	global_load_dword v0, v33, s[30:31] sc1
	s_waitcnt vmcnt(0)
	v_cmp_ge_u32_e32 vcc, v0, v5
	s_orn2_b64 s[30:31], vcc, exec
	s_branch .LBB0_1733
